# baseline (speedup 1.0000x reference)
; #define RAW_BARRIER() do { asm volatile("s_waitcnt lgkmcnt(0)" ::: "memory"); __builtin_amdgcn_s_barrier(); } while (0)
; #define GLDS_TILE(kt, st) do { _Pragma("unroll") for (int _i = 0; _i < NP; ++_i) GLDS_PIECE(_i, kt, st); } while (0)
;     ...
;     constexpr int NH = NI >= 4 ? NI / 2 : NI;
;     constexpr int NP = 2 + NB, IVL = (4 * NI) / NP;
;     RAW_BARRIER();
;     GLDS_TILE(0, 0);
;     GLDS_TILE(1, 1);
;     int st = 0;
;     for (int kt = 0; kt < nk - 1; ++kt) {
;         if (NI == 8) asm volatile("s_waitcnt vmcnt(6)" ::: "memory"); else if (NI == 4) asm volatile("s_waitcnt vmcnt(4)" ::: "memory"); else asm volatile("s_waitcnt vmcnt(3)" ::: "memory");
;         RAW_BARRIER();
;         const int s2 = st >= 1 ? st - 1 : 2;
;         const bool ld = kt + 2 < nk;
;         STEP_TILE(st, ld, kt + 2, s2);
;         st = st == 2 ? 0 : st + 1;
;     }
.LBB0_21:
	s_mul_i32 s28, s23, 0x6000
	s_add_i32 s29, s28, 0
	s_waitcnt vmcnt(6)
	v_add_u32_e32 v148, s29, v134
	v_add_u32_e32 v155, s29, v135
	s_waitcnt lgkmcnt(0)
	s_barrier
	ds_read_b128 v[158:161], v155 offset:8192
	ds_read_b128 v[136:139], v148
	ds_read_b128 v[140:143], v148 offset:1024
	ds_read_b128 v[144:147], v148 offset:2048
	ds_read_b128 v[148:151], v148 offset:3072
	ds_read_b128 v[162:165], v155 offset:9216
	ds_read_b128 v[166:169], v155 offset:10240
	ds_read_b128 v[170:173], v155 offset:11264
	s_addk_i32 s28, 0xa000
	s_cmp_gt_i32 s23, 0
	s_setprio 1
	s_waitcnt lgkmcnt(6)
	v_mfma_f32_16x16x32_bf16 v[126:129], v[158:161], v[136:139], v[126:129]
	s_cselect_b32 s28, s28, 0xc000
	v_add_u32_e32 v157, s28, v32
	v_lshl_add_u64 v[152:153], v[132:133], 0, s[8:9]
	s_waitcnt lgkmcnt(5)
	v_mfma_f32_16x16x32_bf16 v[110:113], v[158:161], v[140:143], v[110:113]
	v_lshl_add_u64 v[208:209], v[130:131], 0, s[8:9]
	s_mov_b64 s[28:29], 0xb52c080
	v_lshl_add_u64 v[206:207], v[152:153], 0, s[30:31]
	s_waitcnt lgkmcnt(4)
	v_mfma_f32_16x16x32_bf16 v[82:85], v[158:161], v[144:147], v[82:85]
	v_add_u32_e32 v205, 0x2000, v157
	s_waitcnt lgkmcnt(3)
	v_mfma_f32_16x16x32_bf16 v[50:53], v[158:161], v[148:151], v[50:53]
	v_lshl_add_u64 v[158:159], v[208:209], 0, s[28:29]
	s_waitcnt lgkmcnt(2)
	v_mfma_f32_16x16x32_bf16 v[122:125], v[162:165], v[136:139], v[122:125]
	v_readfirstlane_b32 s28, v157
	s_mov_b32 m0, s28
	s_nop 0
	global_load_lds_dwordx4 v[158:159], off
	ds_read_b128 v[158:161], v155 offset:12288
	ds_read_b128 v[174:177], v155 offset:13312
	ds_read_b128 v[178:181], v155 offset:14336
	ds_read_b128 v[182:185], v155 offset:15360
	v_mfma_f32_16x16x32_bf16 v[102:105], v[162:165], v[140:143], v[102:105]
	v_mfma_f32_16x16x32_bf16 v[70:73], v[162:165], v[144:147], v[70:73]
	v_mfma_f32_16x16x32_bf16 v[38:41], v[162:165], v[148:151], v[38:41]
	s_waitcnt lgkmcnt(5)
	v_mfma_f32_16x16x32_bf16 v[118:121], v[166:169], v[136:139], v[118:121]
	v_mfma_f32_16x16x32_bf16 v[94:97], v[166:169], v[140:143], v[94:97]
	v_add_u32_e32 v155, 0x1000, v157
	s_mov_b64 s[28:29], 0xb584080
	v_lshl_add_u64 v[162:163], v[208:209], 0, s[28:29]
	v_readfirstlane_b32 s28, v155
	s_mov_b32 m0, s28
	s_nop 0
	global_load_lds_dwordx4 v[162:163], off
	v_mfma_f32_16x16x32_bf16 v[62:65], v[166:169], v[144:147], v[62:65]
	v_mfma_f32_16x16x32_bf16 v[28:31], v[166:169], v[148:151], v[28:31]
	s_waitcnt lgkmcnt(4)
	v_mfma_f32_16x16x32_bf16 v[114:117], v[170:173], v[136:139], v[114:117]
	v_mfma_f32_16x16x32_bf16 v[86:89], v[170:173], v[140:143], v[86:89]
	v_mfma_f32_16x16x32_bf16 v[54:57], v[170:173], v[144:147], v[54:57]
	v_readfirstlane_b32 s28, v205
	s_mov_b32 m0, s28
	s_nop 0
	global_load_lds_dwordx4 v[206:207], off
	v_mfma_f32_16x16x32_bf16 v[20:23], v[170:173], v[148:151], v[20:23]
	s_waitcnt lgkmcnt(0)
	v_mfma_f32_16x16x32_bf16 v[106:109], v[158:161], v[136:139], v[106:109]
	v_mfma_f32_16x16x32_bf16 v[74:77], v[158:161], v[140:143], v[74:77]
	v_mfma_f32_16x16x32_bf16 v[42:45], v[158:161], v[144:147], v[42:45]
	v_mfma_f32_16x16x32_bf16 v[12:15], v[158:161], v[148:151], v[12:15]
	v_add_u32_e32 v155, 0x3000, v157
	s_mov_b64 s[28:29], 0x3558080
	v_lshl_add_u64 v[158:159], v[152:153], 0, s[28:29]
	v_readfirstlane_b32 s28, v155
	s_mov_b32 m0, s28
	s_nop 0
	global_load_lds_dwordx4 v[158:159], off
	v_mfma_f32_16x16x32_bf16 v[98:101], v[174:177], v[136:139], v[98:101]
	v_mfma_f32_16x16x32_bf16 v[66:69], v[174:177], v[140:143], v[66:69]
	v_mfma_f32_16x16x32_bf16 v[34:37], v[174:177], v[144:147], v[34:37]
	v_mfma_f32_16x16x32_bf16 v[8:11], v[174:177], v[148:151], v[8:11]
	v_mfma_f32_16x16x32_bf16 v[90:93], v[178:181], v[136:139], v[90:93]
	v_add_u32_e32 v155, 0x4000, v157
	s_mov_b64 s[28:29], 0x35b0080
	v_lshl_add_u64 v[158:159], v[152:153], 0, s[28:29]
	v_readfirstlane_b32 s28, v155
	s_mov_b32 m0, s28
	s_nop 0
	global_load_lds_dwordx4 v[158:159], off
	v_mfma_f32_16x16x32_bf16 v[58:61], v[178:181], v[140:143], v[58:61]
	v_mfma_f32_16x16x32_bf16 v[24:27], v[178:181], v[144:147], v[24:27]
	v_mfma_f32_16x16x32_bf16 v[4:7], v[178:181], v[148:151], v[4:7]
	v_mfma_f32_16x16x32_bf16 v[78:81], v[182:185], v[136:139], v[78:81]
	v_mfma_f32_16x16x32_bf16 v[46:49], v[182:185], v[140:143], v[46:49]
	v_add_u32_e32 v138, 0x5000, v157
	s_mov_b64 s[28:29], 0x3608080
	v_lshl_add_u64 v[136:137], v[152:153], 0, s[28:29]
	v_readfirstlane_b32 s28, v138
	s_mov_b32 m0, s28
	s_nop 0
	global_load_lds_dwordx4 v[136:137], off
	v_mfma_f32_16x16x32_bf16 v[16:19], v[182:185], v[144:147], v[16:19]
	v_mfma_f32_16x16x32_bf16 v[0:3], v[182:185], v[148:151], v[0:3]
	s_setprio 0
	s_add_i32 s28, s23, 1
	s_cmp_lg_u32 s23, 2
	s_cselect_b32 s23, s28, 0
	s_add_u32 s8, s8, 0x80
	s_addc_u32 s9, s9, 0
	s_cmpk_lg_i32 s8, 0x2b00
	s_cbranch_scc1 .LBB0_21
	s_waitcnt vmcnt(6)
	v_add_u32_e32 v32, 0, v134
	v_add_u32_e32 v152, 0, v135
	s_waitcnt lgkmcnt(0)
	s_barrier
; #define RAW_BARRIER() do { asm volatile("s_waitcnt lgkmcnt(0)" ::: "memory"); __builtin_amdgcn_s_barrier(); } while (0)
;     ...
;     asm volatile("s_waitcnt vmcnt(0)" ::: "memory");
;     RAW_BARRIER();
;     STEP_TILE(st, false, 0, 0);
;     RAW_BARRIER();
	ds_read_b128 v[130:133], v32 offset:49152
	ds_read_b128 v[136:139], v32 offset:50176
	ds_read_b128 v[140:143], v32 offset:51200
	ds_read_b128 v[144:147], v32 offset:52224
	ds_read_b128 v[148:151], v152 offset:57344
	ds_read_b128 v[158:161], v152 offset:58368
	ds_read_b128 v[162:165], v152 offset:59392
	ds_read_b128 v[166:169], v152 offset:60416
	s_setprio 1
	s_waitcnt lgkmcnt(0)
	v_mfma_f32_16x16x32_bf16 v[126:129], v[148:151], v[130:133], v[126:129]
	v_mfma_f32_16x16x32_bf16 v[110:113], v[148:151], v[136:139], v[110:113]
	v_mfma_f32_16x16x32_bf16 v[82:85], v[148:151], v[140:143], v[82:85]
	v_mfma_f32_16x16x32_bf16 v[50:53], v[148:151], v[144:147], v[50:53]
	v_mfma_f32_16x16x32_bf16 v[122:125], v[158:161], v[130:133], v[122:125]
	ds_read_b128 v[148:151], v152 offset:61440
	ds_read_b128 v[170:173], v152 offset:62464
	ds_read_b128 v[174:177], v152 offset:63488
	ds_read_b128 v[178:181], v152 offset:64512
	v_mfma_f32_16x16x32_bf16 v[102:105], v[158:161], v[136:139], v[102:105]
	v_mfma_f32_16x16x32_bf16 v[70:73], v[158:161], v[140:143], v[70:73]
	v_mfma_f32_16x16x32_bf16 v[38:41], v[158:161], v[144:147], v[38:41]
	v_mfma_f32_16x16x32_bf16 v[118:121], v[162:165], v[130:133], v[118:121]
	v_mfma_f32_16x16x32_bf16 v[158:161], v[162:165], v[136:139], v[94:97]
	v_mfma_f32_16x16x32_bf16 v[182:185], v[162:165], v[140:143], v[62:65]
	v_mfma_f32_16x16x32_bf16 v[162:165], v[162:165], v[144:147], v[28:31]
	v_mfma_f32_16x16x32_bf16 v[114:117], v[166:169], v[130:133], v[114:117]
	v_mfma_f32_16x16x32_bf16 v[206:209], v[166:169], v[136:139], v[86:89]
	v_mfma_f32_16x16x32_bf16 v[210:213], v[166:169], v[140:143], v[54:57]
	v_mfma_f32_16x16x32_bf16 v[166:169], v[166:169], v[144:147], v[20:23]
	s_waitcnt lgkmcnt(0)
	v_mfma_f32_16x16x32_bf16 v[106:109], v[148:151], v[130:133], v[106:109]
	v_mfma_f32_16x16x32_bf16 v[74:77], v[148:151], v[136:139], v[74:77]
	v_mfma_f32_16x16x32_bf16 v[42:45], v[148:151], v[140:143], v[42:45]
	v_mfma_f32_16x16x32_bf16 v[12:15], v[148:151], v[144:147], v[12:15]
	v_mfma_f32_16x16x32_bf16 v[98:101], v[170:173], v[130:133], v[98:101]
	v_mfma_f32_16x16x32_bf16 v[66:69], v[170:173], v[136:139], v[66:69]
	v_mfma_f32_16x16x32_bf16 v[34:37], v[170:173], v[140:143], v[34:37]
	v_mfma_f32_16x16x32_bf16 v[8:11], v[170:173], v[144:147], v[8:11]
	v_mfma_f32_16x16x32_bf16 v[148:151], v[174:177], v[130:133], v[90:93]
	v_mfma_f32_16x16x32_bf16 v[170:173], v[174:177], v[136:139], v[58:61]
	v_mfma_f32_16x16x32_bf16 v[214:217], v[174:177], v[140:143], v[24:27]
	v_mfma_f32_16x16x32_bf16 v[4:7], v[174:177], v[144:147], v[4:7]
	v_mfma_f32_16x16x32_bf16 v[130:133], v[178:181], v[130:133], v[78:81]
	v_mfma_f32_16x16x32_bf16 v[134:137], v[178:181], v[136:139], v[46:49]
	v_mfma_f32_16x16x32_bf16 v[138:141], v[178:181], v[140:143], v[16:19]
	v_mfma_f32_16x16x32_bf16 v[0:3], v[178:181], v[144:147], v[0:3]
	s_setprio 0
	s_waitcnt vmcnt(0)
	s_waitcnt lgkmcnt(0)
	s_barrier
	ds_read_b128 v[142:145], v32
	ds_read_b128 v[174:177], v32 offset:1024
	ds_read_b128 v[178:181], v32 offset:2048
	ds_read_b128 v[218:221], v32 offset:3072
	ds_read_b128 v[16:19], v152 offset:8192
	ds_read_b128 v[20:23], v152 offset:9216
	ds_read_b128 v[46:49], v152 offset:10240
	ds_read_b128 v[78:81], v152 offset:11264
	s_setprio 1
	s_waitcnt lgkmcnt(0)
	v_mfma_f32_16x16x32_bf16 v[126:129], v[16:19], v[142:145], v[126:129]
	v_mfma_f32_16x16x32_bf16 v[94:97], v[16:19], v[174:177], v[110:113]
	v_mfma_f32_16x16x32_bf16 v[62:65], v[16:19], v[178:181], v[82:85]
	v_mfma_f32_16x16x32_bf16 v[28:31], v[16:19], v[218:221], v[50:53]
	v_mfma_f32_16x16x32_bf16 v[122:125], v[20:23], v[142:145], v[122:125]
	ds_read_b128 v[110:113], v152 offset:12288
	ds_read_b128 v[222:225], v152 offset:13312
	ds_read_b128 v[226:229], v152 offset:14336
	ds_read_b128 v[230:233], v152 offset:15360
	v_mfma_f32_16x16x32_bf16 v[90:93], v[20:23], v[174:177], v[102:105]
	v_mfma_f32_16x16x32_bf16 v[58:61], v[20:23], v[178:181], v[70:73]
	v_mfma_f32_16x16x32_bf16 v[24:27], v[20:23], v[218:221], v[38:41]
	v_mfma_f32_16x16x32_bf16 v[118:121], v[46:49], v[142:145], v[118:121]
	v_mfma_f32_16x16x32_bf16 v[86:89], v[46:49], v[174:177], v[158:161]
	v_mfma_f32_16x16x32_bf16 v[54:57], v[46:49], v[178:181], v[182:185]
	v_mfma_f32_16x16x32_bf16 v[20:23], v[46:49], v[218:221], v[162:165]
	v_mfma_f32_16x16x32_bf16 v[114:117], v[78:81], v[142:145], v[114:117]
	v_mfma_f32_16x16x32_bf16 v[82:85], v[78:81], v[174:177], v[206:209]
	v_mfma_f32_16x16x32_bf16 v[50:53], v[78:81], v[178:181], v[210:213]
	v_mfma_f32_16x16x32_bf16 v[16:19], v[78:81], v[218:221], v[166:169]
	s_waitcnt lgkmcnt(0)
	v_mfma_f32_16x16x32_bf16 v[158:161], v[110:113], v[142:145], v[106:109]
	v_mfma_f32_16x16x32_bf16 v[78:81], v[110:113], v[174:177], v[74:77]
	v_mfma_f32_16x16x32_bf16 v[46:49], v[110:113], v[178:181], v[42:45]
	v_mfma_f32_16x16x32_bf16 v[12:15], v[110:113], v[218:221], v[12:15]
	v_mfma_f32_16x16x32_bf16 v[162:165], v[222:225], v[142:145], v[98:101]
	v_mfma_f32_16x16x32_bf16 v[74:77], v[222:225], v[174:177], v[66:69]
	v_mfma_f32_16x16x32_bf16 v[42:45], v[222:225], v[178:181], v[34:37]
	v_mfma_f32_16x16x32_bf16 v[8:11], v[222:225], v[218:221], v[8:11]
	v_mfma_f32_16x16x32_bf16 v[102:105], v[226:229], v[142:145], v[148:151]
	v_mfma_f32_16x16x32_bf16 v[70:73], v[226:229], v[174:177], v[170:173]
	v_mfma_f32_16x16x32_bf16 v[38:41], v[226:229], v[178:181], v[214:217]
	v_mfma_f32_16x16x32_bf16 v[4:7], v[226:229], v[218:221], v[4:7]
	v_mfma_f32_16x16x32_bf16 v[98:101], v[230:233], v[142:145], v[130:133]
	v_mfma_f32_16x16x32_bf16 v[66:69], v[230:233], v[174:177], v[134:137]
	v_mfma_f32_16x16x32_bf16 v[34:37], v[230:233], v[178:181], v[138:141]
	v_mfma_f32_16x16x32_bf16 v[0:3], v[230:233], v[218:221], v[0:3]
	s_setprio 0
	v_mov_b32_e32 v32, v186
	s_waitcnt lgkmcnt(0)
	s_barrier
;     __device__ __forceinline__ float* mod() const { return (float*)(ws + OFF_mod); }
; DEV int tid_opaque() { int t = threadIdx.x; asm volatile("" : "+v"(t)); return t; }
; DEV void resid_big(const Params& p, int l, int mt, int nt, const bf16_t* A, int K, const bf16_t* W, int gate_off, bool res_from_input, char* smem) {
;     ...
;     const int t = tid_opaque(), lane = t & 63, wid = t >> 6, wm = wid >> 1, wn = wid & 1, fr = lane & 15, fq = lane >> 4;
;     const int rbase = mt * 128 + wm * 64 + fr, c0 = nt * 256 + wn * 128 + fq * 4;
; #pragma unroll
;     for (int mi = 0; mi < 4; ++mi) {
;         const int row = rbase + mi * 16;
;         const float* gt = p.mod() + (size_t)(l * 9 + mod_index(row)) * 6144 + gate_off + c0;
;         const float* res = res_from_input ? xrow(p, l, row) : p.out + (size_t)row * 1024;
;         float* dst = p.out + (size_t)row * 1024;
; #pragma unroll
;         for (int ni = 0; ni < 8; ++ni) {
;             const f32x4 g4 = *(const f32x4*)(gt + ni * 16), r4 = *(const f32x4*)(res + c0 + ni * 16);
;             *(f32x4*)(dst + c0 + ni * 16) = r4 + g4 * acc[mi][ni];
;         }
;     }
	s_mov_b64 s[28:29], 0x5000
	v_ashrrev_i32_e32 v106, 1, v32
	v_and_b32_e32 v106, 0xffffffc0, v106
	v_lshl_add_u32 v112, s21, 7, v106
	v_and_or_b32 v108, v32, 15, v112
	v_lshlrev_b32_e32 v106, 1, v32
	v_lshrrev_b32_e32 v32, 2, v32
	v_and_b32_e32 v106, 0x80, v106
	v_and_b32_e32 v32, 12, v32
	v_or3_b32 v32, v106, v32, s22
	v_add_u32_e32 v106, 0xffffc000, v112
	v_lshrrev_b32_e32 v106, 4, v106
	s_movk_i32 s22, 0x3fff
	v_or_b32_e32 v106, 1, v106
	v_cmp_lt_i32_e32 vcc, s22, v108
	v_lshlrev_b32_e32 v32, 2, v32
	s_movk_i32 s21, 0x5000
	v_cndmask_b32_e32 v106, 0, v106, vcc
	v_add_u32_e32 v109, s16, v106
	v_mov_b64_e32 v[106:107], s[6:7]
	v_mad_i64_i32 v[110:111], s[8:9], v109, s33, v[106:107]
	v_lshl_add_u64 v[130:131], v[110:111], 0, v[32:33]
	v_ashrrev_i32_e32 v109, 31, v108
	v_lshl_add_u64 v[138:139], v[130:131], 0, s[28:29]
	v_lshlrev_b64 v[110:111], 12, v[108:109]
	v_add_co_u32_e32 v130, vcc, s21, v130
	v_lshl_add_u64 v[110:111], s[92:93], 0, v[110:111]
	s_nop 0
	v_addc_co_u32_e32 v131, vcc, 0, v131, vcc
	v_lshl_add_u64 v[110:111], v[110:111], 0, v[32:33]
	flat_load_dwordx4 v[206:209], v[130:131]
	flat_load_dwordx4 v[210:213], v[138:139] offset:64
	flat_load_dwordx4 v[214:217], v[138:139] offset:128
	flat_load_dwordx4 v[218:221], v[138:139] offset:192
	flat_load_dwordx4 v[222:225], v[138:139] offset:256
	flat_load_dwordx4 v[226:229], v[138:139] offset:320
	flat_load_dwordx4 v[230:233], v[138:139] offset:384
	flat_load_dwordx4 v[234:237], v[138:139] offset:448
	flat_load_dwordx4 v[238:241], v[110:111]
	flat_load_dwordx4 v[242:245], v[110:111] offset:64
	flat_load_dwordx4 v[246:249], v[110:111] offset:128
	flat_load_dwordx4 v[166:169], v[110:111] offset:192
	flat_load_dwordx4 v[170:173], v[110:111] offset:256
	flat_load_dwordx4 v[174:177], v[110:111] offset:320
	flat_load_dwordx4 v[178:181], v[110:111] offset:384
	flat_load_dwordx4 v[182:185], v[110:111] offset:448
	s_waitcnt vmcnt(0) lgkmcnt(0)
	v_pk_fma_f32 v[238:239], v[126:127], v[206:207], v[238:239]
	v_pk_fma_f32 v[240:241], v[128:129], v[208:209], v[240:241]
	v_pk_fma_f32 v[242:243], v[122:123], v[210:211], v[242:243]
	v_pk_fma_f32 v[244:245], v[124:125], v[212:213], v[244:245]
	v_pk_fma_f32 v[246:247], v[118:119], v[214:215], v[246:247]
	v_pk_fma_f32 v[248:249], v[120:121], v[216:217], v[248:249]
	v_pk_fma_f32 v[166:167], v[114:115], v[218:219], v[166:167]
	v_pk_fma_f32 v[168:169], v[116:117], v[220:221], v[168:169]
	v_pk_fma_f32 v[170:171], v[158:159], v[222:223], v[170:171]
	v_pk_fma_f32 v[172:173], v[160:161], v[224:225], v[172:173]
	v_pk_fma_f32 v[174:175], v[162:163], v[226:227], v[174:175]
	v_pk_fma_f32 v[176:177], v[164:165], v[228:229], v[176:177]
	v_pk_fma_f32 v[178:179], v[102:103], v[230:231], v[178:179]
	v_pk_fma_f32 v[180:181], v[104:105], v[232:233], v[180:181]
	v_pk_fma_f32 v[182:183], v[98:99], v[234:235], v[182:183]
	v_pk_fma_f32 v[184:185], v[100:101], v[236:237], v[184:185]
	flat_store_dwordx4 v[110:111], v[238:241]
	flat_store_dwordx4 v[110:111], v[242:245] offset:64
	flat_store_dwordx4 v[110:111], v[246:249] offset:128
	flat_store_dwordx4 v[110:111], v[166:169] offset:192
	flat_store_dwordx4 v[110:111], v[170:173] offset:256
	flat_store_dwordx4 v[110:111], v[174:177] offset:320
	flat_store_dwordx4 v[110:111], v[178:181] offset:384
	flat_store_dwordx4 v[110:111], v[182:185] offset:448
	s_nop 1
	s_add_i32 s17, s17, s18
	s_nop 1
	v_add_u32_e32 v98, 0xffffc010, v112
	v_or_b32_e32 v100, 16, v108
	v_lshrrev_b32_e32 v98, 4, v98
	v_add_u32_e32 v98, 1, v98
	v_cmp_lt_i32_e32 vcc, s22, v100
	v_ashrrev_i32_e32 v101, 31, v100
	v_lshlrev_b64 v[100:101], 12, v[100:101]
	v_cndmask_b32_e32 v98, 0, v98, vcc
	v_add_u32_e32 v98, s16, v98
	v_mad_i64_i32 v[98:99], s[8:9], v98, s33, v[106:107]
	v_lshl_add_u64 v[102:103], v[98:99], 0, v[32:33]
	v_lshl_add_u64 v[98:99], v[102:103], 0, s[28:29]
	v_add_co_u32_e32 v102, vcc, s21, v102
	v_lshl_add_u64 v[100:101], s[92:93], 0, v[100:101]
	s_nop 0
	v_addc_co_u32_e32 v103, vcc, 0, v103, vcc
	v_lshl_add_u64 v[100:101], v[100:101], 0, v[32:33]
	flat_load_dwordx4 v[206:209], v[102:103]
	flat_load_dwordx4 v[210:213], v[98:99] offset:64
	flat_load_dwordx4 v[214:217], v[98:99] offset:128
	flat_load_dwordx4 v[218:221], v[98:99] offset:192
	flat_load_dwordx4 v[222:225], v[98:99] offset:256
	flat_load_dwordx4 v[226:229], v[98:99] offset:320
	flat_load_dwordx4 v[230:233], v[98:99] offset:384
	flat_load_dwordx4 v[234:237], v[98:99] offset:448
	flat_load_dwordx4 v[238:241], v[100:101]
	flat_load_dwordx4 v[242:245], v[100:101] offset:64
	flat_load_dwordx4 v[246:249], v[100:101] offset:128
	flat_load_dwordx4 v[166:169], v[100:101] offset:192
	flat_load_dwordx4 v[170:173], v[100:101] offset:256
	flat_load_dwordx4 v[174:177], v[100:101] offset:320
	flat_load_dwordx4 v[178:181], v[100:101] offset:384
	flat_load_dwordx4 v[182:185], v[100:101] offset:448
	s_waitcnt vmcnt(0) lgkmcnt(0)
;     __device__ __forceinline__ float* mod() const { return (float*)(ws + OFF_mod); }
; DEV int tid_opaque() { int t = threadIdx.x; asm volatile("" : "+v"(t)); return t; }
; DEV void resid_big(const Params& p, int l, int mt, int nt, const bf16_t* A, int K, const bf16_t* W, int gate_off, bool res_from_input, char* smem) {
;     ...
;     const int t = tid_opaque(), lane = t & 63, wid = t >> 6, wm = wid >> 1, wn = wid & 1, fr = lane & 15, fq = lane >> 4;
;     const int rbase = mt * 128 + wm * 64 + fr, c0 = nt * 256 + wn * 128 + fq * 4;
; #pragma unroll
;     for (int mi = 0; mi < 4; ++mi) {
;         const int row = rbase + mi * 16;
;         const float* gt = p.mod() + (size_t)(l * 9 + mod_index(row)) * 6144 + gate_off + c0;
;         const float* res = res_from_input ? xrow(p, l, row) : p.out + (size_t)row * 1024;
;         float* dst = p.out + (size_t)row * 1024;
; #pragma unroll
;         for (int ni = 0; ni < 8; ++ni) {
;             const f32x4 g4 = *(const f32x4*)(gt + ni * 16), r4 = *(const f32x4*)(res + c0 + ni * 16);
;             *(f32x4*)(dst + c0 + ni * 16) = r4 + g4 * acc[mi][ni];
;         }
;     }
	v_pk_fma_f32 v[238:239], v[94:95], v[206:207], v[238:239]
	v_pk_fma_f32 v[240:241], v[96:97], v[208:209], v[240:241]
	v_pk_fma_f32 v[242:243], v[90:91], v[210:211], v[242:243]
	v_pk_fma_f32 v[244:245], v[92:93], v[212:213], v[244:245]
	v_pk_fma_f32 v[246:247], v[86:87], v[214:215], v[246:247]
	v_pk_fma_f32 v[248:249], v[88:89], v[216:217], v[248:249]
	v_pk_fma_f32 v[166:167], v[82:83], v[218:219], v[166:167]
	v_pk_fma_f32 v[168:169], v[84:85], v[220:221], v[168:169]
	v_pk_fma_f32 v[170:171], v[78:79], v[222:223], v[170:171]
	v_pk_fma_f32 v[172:173], v[80:81], v[224:225], v[172:173]
	v_pk_fma_f32 v[174:175], v[74:75], v[226:227], v[174:175]
	v_pk_fma_f32 v[176:177], v[76:77], v[228:229], v[176:177]
	v_pk_fma_f32 v[178:179], v[70:71], v[230:231], v[178:179]
	v_pk_fma_f32 v[180:181], v[72:73], v[232:233], v[180:181]
	v_pk_fma_f32 v[182:183], v[66:67], v[234:235], v[182:183]
	v_pk_fma_f32 v[184:185], v[68:69], v[236:237], v[184:185]
	flat_store_dwordx4 v[100:101], v[238:241]
	flat_store_dwordx4 v[100:101], v[242:245] offset:64
	flat_store_dwordx4 v[100:101], v[246:249] offset:128
	flat_store_dwordx4 v[100:101], v[166:169] offset:192
	flat_store_dwordx4 v[100:101], v[170:173] offset:256
	flat_store_dwordx4 v[100:101], v[174:177] offset:320
	flat_store_dwordx4 v[100:101], v[178:181] offset:384
	flat_store_dwordx4 v[100:101], v[182:185] offset:448
	s_nop 1
	s_nop 1
	v_add_u32_e32 v66, 0xffffc020, v112
	v_or_b32_e32 v68, 32, v108
	v_lshrrev_b32_e32 v66, 4, v66
	v_or_b32_e32 v66, 1, v66
	v_cmp_lt_i32_e32 vcc, s22, v68
	v_ashrrev_i32_e32 v69, 31, v68
	v_lshlrev_b64 v[68:69], 12, v[68:69]
	v_cndmask_b32_e32 v66, 0, v66, vcc
	v_add_u32_e32 v66, s16, v66
	v_mad_i64_i32 v[66:67], s[8:9], v66, s33, v[106:107]
	v_lshl_add_u64 v[70:71], v[66:67], 0, v[32:33]
	v_lshl_add_u64 v[66:67], v[70:71], 0, s[28:29]
	v_add_co_u32_e32 v70, vcc, s21, v70
	v_lshl_add_u64 v[68:69], s[92:93], 0, v[68:69]
	s_nop 0
	v_addc_co_u32_e32 v71, vcc, 0, v71, vcc
	v_lshl_add_u64 v[68:69], v[68:69], 0, v[32:33]
	flat_load_dwordx4 v[206:209], v[70:71]
	flat_load_dwordx4 v[210:213], v[66:67] offset:64
	flat_load_dwordx4 v[214:217], v[66:67] offset:128
	flat_load_dwordx4 v[218:221], v[66:67] offset:192
	flat_load_dwordx4 v[222:225], v[66:67] offset:256
	flat_load_dwordx4 v[226:229], v[66:67] offset:320
	flat_load_dwordx4 v[230:233], v[66:67] offset:384
	flat_load_dwordx4 v[234:237], v[66:67] offset:448
	flat_load_dwordx4 v[238:241], v[68:69]
	flat_load_dwordx4 v[242:245], v[68:69] offset:64
	flat_load_dwordx4 v[246:249], v[68:69] offset:128
	flat_load_dwordx4 v[166:169], v[68:69] offset:192
	flat_load_dwordx4 v[170:173], v[68:69] offset:256
	flat_load_dwordx4 v[174:177], v[68:69] offset:320
	flat_load_dwordx4 v[178:181], v[68:69] offset:384
	flat_load_dwordx4 v[182:185], v[68:69] offset:448
	s_waitcnt vmcnt(0) lgkmcnt(0)
;     __device__ __forceinline__ float* mod() const { return (float*)(ws + OFF_mod); }
; DEV void resid_big(const Params& p, int l, int mt, int nt, const bf16_t* A, int K, const bf16_t* W, int gate_off, bool res_from_input, char* smem) {
;     ...
;     for (int mi = 0; mi < 4; ++mi) {
;         const int row = rbase + mi * 16;
;         const float* gt = p.mod() + (size_t)(l * 9 + mod_index(row)) * 6144 + gate_off + c0;
;         const float* res = res_from_input ? xrow(p, l, row) : p.out + (size_t)row * 1024;
;         float* dst = p.out + (size_t)row * 1024;
; #pragma unroll
;         for (int ni = 0; ni < 8; ++ni) {
;             const f32x4 g4 = *(const f32x4*)(gt + ni * 16), r4 = *(const f32x4*)(res + c0 + ni * 16);
;             *(f32x4*)(dst + c0 + ni * 16) = r4 + g4 * acc[mi][ni];
;         }
;     }
	v_pk_fma_f32 v[238:239], v[62:63], v[206:207], v[238:239]
	v_pk_fma_f32 v[240:241], v[64:65], v[208:209], v[240:241]
	v_pk_fma_f32 v[242:243], v[58:59], v[210:211], v[242:243]
	v_pk_fma_f32 v[244:245], v[60:61], v[212:213], v[244:245]
	v_pk_fma_f32 v[246:247], v[54:55], v[214:215], v[246:247]
	v_pk_fma_f32 v[248:249], v[56:57], v[216:217], v[248:249]
	v_pk_fma_f32 v[166:167], v[50:51], v[218:219], v[166:167]
	v_pk_fma_f32 v[168:169], v[52:53], v[220:221], v[168:169]
	v_pk_fma_f32 v[170:171], v[46:47], v[222:223], v[170:171]
	v_pk_fma_f32 v[172:173], v[48:49], v[224:225], v[172:173]
	v_pk_fma_f32 v[174:175], v[42:43], v[226:227], v[174:175]
	v_pk_fma_f32 v[176:177], v[44:45], v[228:229], v[176:177]
	v_pk_fma_f32 v[178:179], v[38:39], v[230:231], v[178:179]
	v_pk_fma_f32 v[180:181], v[40:41], v[232:233], v[180:181]
	v_pk_fma_f32 v[182:183], v[34:35], v[234:235], v[182:183]
	v_pk_fma_f32 v[184:185], v[36:37], v[236:237], v[184:185]
	flat_store_dwordx4 v[68:69], v[238:241]
	flat_store_dwordx4 v[68:69], v[242:245] offset:64
	flat_store_dwordx4 v[68:69], v[246:249] offset:128
	flat_store_dwordx4 v[68:69], v[166:169] offset:192
	flat_store_dwordx4 v[68:69], v[170:173] offset:256
	flat_store_dwordx4 v[68:69], v[174:177] offset:320
	flat_store_dwordx4 v[68:69], v[178:181] offset:384
	flat_store_dwordx4 v[68:69], v[182:185] offset:448
	s_nop 1
	v_add_u32_e32 v40, 0xffffc030, v112
	s_nop 0
	v_or_b32_e32 v34, 48, v108
	v_ashrrev_i32_e32 v35, 31, v34
	v_lshlrev_b64 v[36:37], 12, v[34:35]
	v_lshrrev_b32_e32 v35, 4, v40
	v_add_u32_e32 v35, 1, v35
	v_cmp_lt_i32_e32 vcc, s22, v34
	v_lshl_add_u64 v[38:39], s[92:93], 0, v[36:37]
	s_nop 0
	v_cndmask_b32_e32 v34, 0, v35, vcc
	v_add_u32_e32 v34, s16, v34
	v_mad_i64_i32 v[34:35], s[8:9], v34, s33, v[106:107]
	v_lshl_add_u64 v[40:41], v[34:35], 0, v[32:33]
	v_lshl_add_u64 v[34:35], v[38:39], 0, v[32:33]
	v_add_co_u32_e32 v38, vcc, s21, v40
	v_lshl_add_u64 v[36:37], v[40:41], 0, s[28:29]
	s_nop 0
	v_addc_co_u32_e32 v39, vcc, 0, v41, vcc
	flat_load_dwordx4 v[206:209], v[38:39]
	flat_load_dwordx4 v[210:213], v[36:37] offset:64
	flat_load_dwordx4 v[214:217], v[36:37] offset:128
	flat_load_dwordx4 v[218:221], v[36:37] offset:192
	flat_load_dwordx4 v[222:225], v[36:37] offset:256
	flat_load_dwordx4 v[226:229], v[36:37] offset:320
	flat_load_dwordx4 v[230:233], v[36:37] offset:384
	flat_load_dwordx4 v[234:237], v[36:37] offset:448
	flat_load_dwordx4 v[238:241], v[34:35]
	flat_load_dwordx4 v[242:245], v[34:35] offset:64
	flat_load_dwordx4 v[246:249], v[34:35] offset:128
	flat_load_dwordx4 v[166:169], v[34:35] offset:192
	flat_load_dwordx4 v[170:173], v[34:35] offset:256
	flat_load_dwordx4 v[174:177], v[34:35] offset:320
	flat_load_dwordx4 v[178:181], v[34:35] offset:384
	flat_load_dwordx4 v[182:185], v[34:35] offset:448
	s_waitcnt vmcnt(0) lgkmcnt(0)
	v_pk_fma_f32 v[238:239], v[28:29], v[206:207], v[238:239]
	v_pk_fma_f32 v[240:241], v[30:31], v[208:209], v[240:241]
	v_pk_fma_f32 v[242:243], v[24:25], v[210:211], v[242:243]
	v_pk_fma_f32 v[244:245], v[26:27], v[212:213], v[244:245]
	v_pk_fma_f32 v[246:247], v[20:21], v[214:215], v[246:247]
	v_pk_fma_f32 v[248:249], v[22:23], v[216:217], v[248:249]
	v_pk_fma_f32 v[166:167], v[16:17], v[218:219], v[166:167]
	v_pk_fma_f32 v[168:169], v[18:19], v[220:221], v[168:169]
	v_pk_fma_f32 v[170:171], v[12:13], v[222:223], v[170:171]
	v_pk_fma_f32 v[172:173], v[14:15], v[224:225], v[172:173]
	v_pk_fma_f32 v[174:175], v[8:9], v[226:227], v[174:175]
	v_pk_fma_f32 v[176:177], v[10:11], v[228:229], v[176:177]
	v_pk_fma_f32 v[178:179], v[4:5], v[230:231], v[178:179]
	v_pk_fma_f32 v[180:181], v[6:7], v[232:233], v[180:181]
	v_pk_fma_f32 v[182:183], v[0:1], v[234:235], v[182:183]
	v_pk_fma_f32 v[184:185], v[2:3], v[236:237], v[184:185]
	flat_store_dwordx4 v[34:35], v[238:241]
	flat_store_dwordx4 v[34:35], v[242:245] offset:64
	flat_store_dwordx4 v[34:35], v[246:249] offset:128
	flat_store_dwordx4 v[34:35], v[166:169] offset:192
	flat_store_dwordx4 v[34:35], v[170:173] offset:256
	flat_store_dwordx4 v[34:35], v[174:177] offset:320
	flat_store_dwordx4 v[34:35], v[178:181] offset:384
	flat_store_dwordx4 v[34:35], v[182:185] offset:448
	s_nop 1
	v_readlane_b32 s8, v254, 4
	s_add_i32 s20, s20, s8
	s_add_i32 s19, s19, s8
	s_cmpk_gt_i32 s20, 0x1ff
	v_readlane_b32 s9, v254, 5
	s_cbranch_scc0 .LBB0_20
